# MLA loop: next-tile K/V global loads in saddr form with 32-bit lane offsets (18 -> 8 VALU, no v_mad_i64)
# baseline (speedup 1.0000x reference)
.LBB0_750:
	v_sub_f32_e32 v96, v96, v14
	v_sub_f32_e32 v97, v97, v14
	v_sub_f32_e32 v98, v98, v14
	v_sub_f32_e32 v99, v99, v14
	v_sub_f32_e32 v100, v100, v14
	v_sub_f32_e32 v101, v101, v14
	v_sub_f32_e32 v102, v102, v14
	v_sub_f32_e32 v103, v103, v14
	v_exp_f32_e32 v96, v96
	v_exp_f32_e32 v97, v97
	v_exp_f32_e32 v98, v98
	v_exp_f32_e32 v99, v99
	v_exp_f32_e32 v100, v100
	v_exp_f32_e32 v101, v101
	v_exp_f32_e32 v102, v102
	v_exp_f32_e32 v103, v103
	v_cvt_pk_bf16_f32 v236, v96, v97
	v_cvt_pk_bf16_f32 v237, v98, v99
	v_cvt_pk_bf16_f32 v238, v100, v101
	v_cvt_pk_bf16_f32 v239, v102, v103
	v_sub_f32_e32 v104, v104, v14
	v_sub_f32_e32 v105, v105, v14
	v_mfma_f32_32x32x16_bf16 v[32:47], v[6:9], v[236:239], v[32:47]
	v_sub_f32_e32 v106, v106, v14
	v_sub_f32_e32 v107, v107, v14
	v_sub_f32_e32 v108, v108, v14
	v_sub_f32_e32 v109, v109, v14
	v_sub_f32_e32 v110, v110, v14
	v_sub_f32_e32 v111, v111, v14
	v_exp_f32_e32 v104, v104
	v_mfma_f32_32x32x16_bf16 v[16:31], v[10:13], v[236:239], v[16:31]
	v_exp_f32_e32 v105, v105
	v_exp_f32_e32 v106, v106
	v_exp_f32_e32 v107, v107
	v_exp_f32_e32 v108, v108
	v_exp_f32_e32 v109, v109
	v_exp_f32_e32 v110, v110
	v_exp_f32_e32 v111, v111
	v_sub_f32_e32 v7, v82, v14
	v_sub_f32_e32 v8, v83, v14
	v_sub_f32_e32 v9, v84, v14
	v_sub_f32_e32 v10, v85, v14
	v_cvt_pk_bf16_f32 v82, v104, v105
	v_cvt_pk_bf16_f32 v83, v106, v107
	v_cvt_pk_bf16_f32 v84, v108, v109
	v_cvt_pk_bf16_f32 v85, v110, v111
	v_sub_f32_e32 v80, v80, v14
	v_sub_f32_e32 v6, v81, v14
	v_mfma_f32_32x32x16_bf16 v[32:47], v[2:5], v[82:85], v[32:47]
	v_sub_f32_e32 v2, v86, v14
	v_sub_f32_e32 v3, v87, v14
	v_exp_f32_e32 v80, v80
	v_exp_f32_e32 v6, v6
	v_exp_f32_e32 v7, v7
	v_exp_f32_e32 v8, v8
	v_exp_f32_e32 v9, v9
	v_mfma_f32_32x32x16_bf16 v[16:31], v[112:115], v[82:85], v[16:31]
	v_exp_f32_e32 v10, v10
	v_exp_f32_e32 v2, v2
	v_exp_f32_e32 v3, v3
	v_cvt_pk_bf16_f32 v82, v80, v6
	v_cvt_pk_bf16_f32 v83, v7, v8
	v_cvt_pk_bf16_f32 v84, v9, v10
	v_cvt_pk_bf16_f32 v85, v2, v3
	v_sub_f32_e32 v4, v88, v14
	v_sub_f32_e32 v5, v89, v14
	v_mfma_f32_32x32x16_bf16 v[32:47], v[116:119], v[82:85], v[32:47]
	v_sub_f32_e32 v11, v90, v14
	v_sub_f32_e32 v12, v91, v14
	v_sub_f32_e32 v13, v92, v14
	v_sub_f32_e32 v81, v93, v14
	v_sub_f32_e32 v86, v94, v14
	v_exp_f32_e32 v4, v4
	v_exp_f32_e32 v5, v5
	v_mfma_f32_32x32x16_bf16 v[16:31], v[120:123], v[82:85], v[16:31]
	v_sub_f32_e32 v83, v95, v14
	v_exp_f32_e32 v11, v11
	v_exp_f32_e32 v12, v12
	v_exp_f32_e32 v13, v13
	v_exp_f32_e32 v81, v81
	v_exp_f32_e32 v82, v86
	v_exp_f32_e32 v83, v83
	v_cvt_pk_bf16_f32 v84, v4, v5
	v_cvt_pk_bf16_f32 v85, v11, v12
	v_cvt_pk_bf16_f32 v86, v13, v81
	v_cvt_pk_bf16_f32 v87, v82, v83
	s_add_i32 s12, s11, 1
	s_cmp_gt_u32 s11, 34
	v_mfma_f32_32x32x16_bf16 v[32:47], v[124:127], v[84:87], v[32:47]
	s_movk_i32 s14, 0xd0
	v_mfma_f32_32x32x16_bf16 v[16:31], v[128:131], v[84:87], v[16:31]
	s_cbranch_scc1 .LBB0_753
	s_bitcmp1_b32 s12, 0
	s_cselect_b32 s11, 0x5800, 0
	v_add_u32_e32 v84, s11, v204
	v_add_u32_e32 v85, s11, v205
	v_add_u32_e32 v86, s11, v209
	v_add_u32_e32 v87, s11, v212
	v_add_u32_e32 v88, s11, v235
	s_waitcnt vmcnt(4)
	ds_write_b128 v84, v[168:171]
	s_waitcnt vmcnt(3)
	ds_write_b128 v85, v[172:175]
	s_waitcnt vmcnt(2)
	ds_write_b128 v86, v[176:179]
	s_waitcnt vmcnt(1)
	ds_write_b128 v87, v[180:183] offset:13312
	s_waitcnt vmcnt(0)
	ds_write_b128 v88, v[184:187] offset:13312
	s_cmp_eq_u32 s6, 0x66000
	s_cbranch_scc1 .LBB0_753
	s_add_u32 s14, s9, s6
	s_addc_u32 s15, s10, s7
	v_lshlrev_b32_e32 v84, 4, v193
	v_add_u32_e32 v85, 0x1000, v84
	v_add_u32_e32 v86, s16, v84
	v_lshrrev_b32_e32 v87, 3, v193
	v_and_b32_e32 v88, 0x70, v84
	v_mul_u32_u24_e32 v87, 0x1200, v87
	s_movk_i32 s11, 0x1200
	global_load_dwordx4 v[168:171], v84, s[14:15]
	global_load_dwordx4 v[172:175], v85, s[14:15]
	global_load_dwordx4 v[176:179], v86, s[14:15]
	v_or_b32_e32 v87, v87, v88
	v_add_u32_e32 v88, 0x24000, v87
	s_nop 0
	global_load_dwordx4 v[180:183], v87, s[0:1]
	global_load_dwordx4 v[184:187], v88, s[0:1]
